# MoE down and combine phases reuse the expert tile tables left in LDS by the up phase instead of rebuilding them
# speedup vs baseline: 1.0026x; 1.0026x over previous
.LBB0_1022:
	s_mov_b64 s[2:3], s[0:1]
	s_load_dwordx2 s[4:5], s[2:3], 0x98
	s_getreg_b32 s2, hwreg(HW_REG_HW_ID, 0, 6)
	s_and_b32 s2, s2, 63
	s_lshl_b32 s2, s2, 2
	s_or_b32 s2, s2, 0x20100
	v_mov_b32_e32 v0, s2
	ds_read_b32 v0, v0
	s_waitcnt lgkmcnt(0)
	v_readfirstlane_b32 s14, v0
	v_mov_b32_e32 v0, v213
	s_lshl_b32 s34, s14, 6
	v_mbcnt_lo_u32_b32 v0, -1, v0
	v_mbcnt_hi_u32_b32 v0, -1, v0
	v_add_u32_e32 v0, s34, v0
	s_nop 0
	v_cmp_gt_i32_e32 vcc, 64, v0
	s_and_saveexec_b64 s[6:7], vcc
	v_readlane_b32 s16, v254, 51
	v_readlane_b32 s17, v254, 52
	s_mov_b32 s77, 0x20000
	v_readlane_b32 s16, v254, 61
	s_branch .LBB0_1041

.LBB0_1121:
	s_mov_b64 s[2:3], s[0:1]
	s_load_dwordx2 s[24:25], s[2:3], 0x40
	s_mov_b64 s[2:3], s[0:1]
	s_load_dwordx2 s[22:23], s[2:3], 0x48
	s_mov_b64 s[2:3], s[0:1]
	s_load_dwordx2 s[20:21], s[2:3], 0x50
	s_mov_b64 s[2:3], s[0:1]
	v_mov_b32_e32 v0, v213
	s_load_dwordx2 s[16:17], s[2:3], 0x58
	s_lshl_b32 s2, s34, 6
	v_mbcnt_lo_u32_b32 v0, -1, v0
	v_mbcnt_hi_u32_b32 v0, -1, v0
	v_add_u32_e32 v32, s2, v0
	v_mov_b32_e32 v0, v213
	s_nop 0
	v_mbcnt_lo_u32_b32 v0, -1, v0
	v_mbcnt_hi_u32_b32 v0, -1, v0
	v_add_u32_e32 v0, s2, v0
	s_nop 0
	v_cmp_gt_i32_e32 vcc, 64, v0
	s_and_saveexec_b64 s[26:27], vcc
	v_readlane_b32 s74, v254, 51
	v_readlane_b32 s71, v254, 58
	v_readlane_b32 s75, v254, 52
	v_readlane_b32 s81, v254, 59
	v_readlane_b32 s83, v254, 60
	v_readlane_b32 s64, v254, 55
	s_mov_b32 s93, 0x18000
	s_mov_b32 s65, 0x30000
	s_movk_i32 s66, 0x210
	s_branch .LBB0_1140
